# v21: v9 + prompt-attention items remapped so the 8 query tiles that share a K/V image run on the same XCD (item = (blockIdx&7)*32 + blockIdx>>3)
# baseline (speedup 1.0000x reference)
; DI void attn_prompt_item(const Params& p, int item, ldsp lds, int tid_) {
;     ...
;   const int wid = __builtin_amdgcn_readfirstlane(tid >> 6), lane = tid & 63, l31 = lane & 31, h2 = lane >> 5;
;   const int b = item >> 5, h = (item >> 3) & 3, qt = item & 7;
;   bf16_t* qx = (bf16_t*)(p.ws + B_QX);
;   const bf16_t* mkb = (const bf16_t*)(p.ws + B_MKB);
;   const bf16_t* mvt = (const bf16_t*)(p.ws + B_MVT);
;   const size_t qrow = (size_t)b * 2048 + qt * 256 + wid * 32 + l31;
; DI void phase_attn(const Params& p, ldsp lds, int tid) {
;     ...
;   for (int i = blockIdx.x; i < 256; i += G) attn_prompt_item(p, i, lds, tid);
.LBB0_1670:
	s_cmpk_gt_i32 s2, 0xff
	s_cbranch_scc1 .LBB0_1673
	s_add_u32 s4, s42, 0xfb40000
	s_addc_u32 s5, s43, 0
	s_add_u32 s0, s42, 0xb140000
	s_addc_u32 s1, s43, 0
	v_mbcnt_hi_u32_b32 v168, -1, v213
	s_add_u32 s6, s42, 0xb540000
	v_and_b32_e32 v0, 64, v168
	s_addc_u32 s7, s43, 0
	s_and_b32 s99, s2, 7
	s_lshl_b32 s99, s99, 5
	s_lshr_b32 s98, s2, 3
	s_or_b32 s99, s99, s98
	s_lshl_b32 s30, s99, 5
	s_lshl_b32 s31, s94, 5
	s_lshl_b32 s33, s99, 8
	s_lshl_b32 s34, s94, 8
	s_mov_b32 s27, 0
	v_mov_b32_e32 v161, 0
	s_mov_b32 s35, 0xf149f2ca
	v_xor_b32_e32 v169, 32, v168
	v_add_u32_e32 v170, 64, v0
	v_mov_b32_e32 v171, 0xf0
	s_mov_b32 s38, 0x2100000
	s_add_i32 s39, 16, 0x10000
	s_add_i32 s40, 16, 0x14000
	s_add_i32 s41, 16, 0x18000
	s_add_i32 s44, 16, 0x1c000
	s_mov_b32 s45, s99
